# grid barrier: pollers wait on the monotonic cross-XCC arrival counter reaching (gen+1)*nx, so the last leader's arrival atomic is the release
# speedup vs baseline: 1.0032x; 1.0032x over previous
.LBB0_115:
	s_or_b64 exec, exec, s[12:13]
	v_cvt_f32_u32_e32 v4, v2
	s_waitcnt vmcnt(0)
	v_readfirstlane_b32 s6, v3
	v_sub_u32_e32 v3, 0, v2
	v_rcp_iflag_f32_e32 v4, v4
	v_add_u32_e32 v5, s6, v1
	v_mul_f32_e32 v4, 0x4f7ffffe, v4
	v_cvt_u32_f32_e32 v4, v4
	v_mul_lo_u32 v1, v3, v4
	v_mul_hi_u32 v1, v4, v1
	v_add_u32_e32 v1, v4, v1
	v_mul_hi_u32 v1, v5, v1
	v_mul_lo_u32 v3, v1, v2
	v_sub_u32_e32 v3, v5, v3
	v_add_u32_e32 v4, 1, v1
	v_sub_u32_e32 v6, v3, v2
	v_cmp_ge_u32_e32 vcc, v3, v2
	s_nop 1
	v_cndmask_b32_e32 v1, v1, v4, vcc
	v_cndmask_b32_e32 v3, v3, v6, vcc
	v_add_u32_e32 v4, 1, v1
	v_cmp_ge_u32_e32 vcc, v3, v2
	v_add_u32_e32 v3, 1, v5
	s_nop 0
	v_cndmask_b32_e32 v1, v1, v4, vcc
	v_mul_lo_u32 v4, v2, v1
	v_add_u32_e32 v2, v4, v2
	v_cmp_ne_u32_e32 vcc, v3, v2
	s_and_saveexec_b64 s[6:7], vcc
	s_xor_b64 s[12:13], exec, s[6:7]
	s_cbranch_execz .LBB0_129
	v_readlane_b32 s100, v252, 9
	s_nop 3
	v_mov_b32_e32 v18, s100
	ds_read_b32 v18, v18
	v_add_u32_e32 v19, 1, v1
	s_waitcnt lgkmcnt(0)
	v_mul_lo_u32 v18, v18, v19
	v_readlane_b32 s6, v253, 20
	v_readlane_b32 s7, v253, 21
	s_waitcnt lgkmcnt(0)
	s_nop 3
	buffer_inv sc1
	global_load_dword v0, v64, s[6:7] sc1
	s_waitcnt vmcnt(0)
	v_cmp_lt_u32_e32 vcc, v0, v18
	s_and_saveexec_b64 s[16:17], vcc
	s_cbranch_execz .LBB0_128
	s_mov_b32 s6, 1
	s_mov_b64 s[20:21], 0
	s_branch .LBB0_119

.LBB0_121:
	v_readlane_b32 s38, v253, 20
	v_readlane_b32 s39, v253, 21
	s_add_i32 s6, s6, 1
	s_mov_b64 s[40:41], -1
	s_nop 2
	global_load_dword v0, v64, s[38:39] sc1
	s_waitcnt vmcnt(0)
	v_cmp_ge_u32_e32 vcc, v0, v18
	s_orn2_b64 s[38:39], vcc, exec
	s_branch .LBB0_118

.LBB0_132:
	s_or_b64 exec, exec, s[16:17]
	v_cvt_f32_u32_e32 v3, v0
	s_waitcnt vmcnt(0)
	v_readfirstlane_b32 s6, v2
	v_sub_u32_e32 v2, 0, v0
	s_mov_b64 s[16:17], -1
	v_rcp_iflag_f32_e32 v3, v3
	v_add_u32_e32 v1, s6, v1
	v_add_u32_e32 v4, 1, v1
	v_readlane_b32 s6, v253, 22
	v_mul_f32_e32 v3, 0x4f7ffffe, v3
	v_cvt_u32_f32_e32 v3, v3
	v_readlane_b32 s7, v253, 23
	v_mul_lo_u32 v2, v2, v3
	v_mul_hi_u32 v2, v3, v2
	v_add_u32_e32 v2, v3, v2
	v_mul_hi_u32 v2, v1, v2
	v_mul_lo_u32 v3, v2, v0
	v_sub_u32_e32 v1, v1, v3
	v_add_u32_e32 v5, 1, v2
	v_sub_u32_e32 v3, v1, v0
	v_cmp_ge_u32_e32 vcc, v1, v0
	s_nop 1
	v_cndmask_b32_e32 v2, v2, v5, vcc
	v_cndmask_b32_e32 v1, v1, v3, vcc
	v_add_u32_e32 v3, 1, v2
	v_cmp_ge_u32_e32 vcc, v1, v0
	s_nop 1
	v_cndmask_b32_e32 v2, v2, v3, vcc
	v_mul_lo_u32 v1, v0, v2
	v_add_u32_e32 v0, v1, v0
	v_cmp_ne_u32_e32 vcc, v4, v0
	v_mov_b64_e32 v[0:1], s[6:7]
	s_and_saveexec_b64 s[12:13], vcc
	s_cbranch_execz .LBB0_144
	v_readlane_b32 s100, v252, 9
	s_nop 3
	v_mov_b32_e32 v18, s100
	ds_read_b32 v18, v18
	v_add_u32_e32 v19, 1, v2
	s_waitcnt lgkmcnt(0)
	v_mul_lo_u32 v18, v18, v19
	v_readlane_b32 s6, v253, 20
	v_readlane_b32 s7, v253, 21
	s_mov_b64 s[20:21], 0
	s_nop 3
	global_load_dword v0, v64, s[6:7] sc1
	s_waitcnt vmcnt(0)
	v_cmp_lt_u32_e32 vcc, v0, v18
	s_and_saveexec_b64 s[16:17], vcc
	s_cbranch_execz .LBB0_143
	s_mov_b32 s6, 1
	s_branch .LBB0_136

.LBB0_1155:
	s_or_b64 exec, exec, s[12:13]
	v_cvt_f32_u32_e32 v4, v2
	s_waitcnt vmcnt(0)
	v_readfirstlane_b32 s6, v3
	v_sub_u32_e32 v3, 0, v2
	v_rcp_iflag_f32_e32 v4, v4
	v_add_u32_e32 v5, s6, v1
	v_mul_f32_e32 v4, 0x4f7ffffe, v4
	v_cvt_u32_f32_e32 v4, v4
	v_mul_lo_u32 v1, v3, v4
	v_mul_hi_u32 v1, v4, v1
	v_add_u32_e32 v1, v4, v1
	v_mul_hi_u32 v1, v5, v1
	v_mul_lo_u32 v3, v1, v2
	v_sub_u32_e32 v3, v5, v3
	v_add_u32_e32 v4, 1, v1
	v_cmp_ge_u32_e32 vcc, v3, v2
	s_nop 1
	v_cndmask_b32_e32 v1, v1, v4, vcc
	v_sub_u32_e32 v4, v3, v2
	v_cndmask_b32_e32 v3, v3, v4, vcc
	v_add_u32_e32 v4, 1, v1
	v_cmp_ge_u32_e32 vcc, v3, v2
	v_add_u32_e32 v3, 1, v5
	s_nop 0
	v_cndmask_b32_e32 v1, v1, v4, vcc
	v_mul_lo_u32 v4, v2, v1
	v_add_u32_e32 v2, v4, v2
	v_cmp_ne_u32_e32 vcc, v3, v2
	s_and_saveexec_b64 s[6:7], vcc
	s_xor_b64 s[12:13], exec, s[6:7]
	s_cbranch_execz .LBB0_1169
	v_readlane_b32 s100, v252, 9
	s_nop 3
	v_mov_b32_e32 v18, s100
	ds_read_b32 v18, v18
	v_add_u32_e32 v19, 1, v1
	s_waitcnt lgkmcnt(0)
	v_mul_lo_u32 v18, v18, v19
	v_readlane_b32 s6, v253, 20
	v_readlane_b32 s7, v253, 21
	s_waitcnt lgkmcnt(0)
	s_nop 3
	buffer_inv sc1
	global_load_dword v0, v64, s[6:7] sc1
	s_waitcnt vmcnt(0)
	v_cmp_lt_u32_e32 vcc, v0, v18
	s_and_saveexec_b64 s[16:17], vcc
	s_cbranch_execz .LBB0_1168
	s_mov_b32 s6, 1
	s_mov_b64 s[20:21], 0
	s_branch .LBB0_1159

.LBB0_1172:
	s_or_b64 exec, exec, s[16:17]
	s_waitcnt vmcnt(0)
	v_readfirstlane_b32 s6, v2
	v_cvt_f32_u32_e32 v2, v0
	v_sub_u32_e32 v3, 0, v0
	v_add_u32_e32 v1, s6, v1
	v_readlane_b32 s6, v253, 22
	v_rcp_iflag_f32_e32 v2, v2
	v_readlane_b32 s7, v253, 23
	s_mov_b64 s[16:17], -1
	v_mul_f32_e32 v2, 0x4f7ffffe, v2
	v_cvt_u32_f32_e32 v2, v2
	v_mul_lo_u32 v3, v3, v2
	v_mul_hi_u32 v3, v2, v3
	v_add_u32_e32 v2, v2, v3
	v_mul_hi_u32 v2, v1, v2
	v_mul_lo_u32 v3, v2, v0
	v_sub_u32_e32 v3, v1, v3
	v_cmp_ge_u32_e32 vcc, v3, v0
	v_add_u32_e32 v4, 1, v2
	v_add_u32_e32 v1, 1, v1
	v_cndmask_b32_e32 v2, v2, v4, vcc
	v_sub_u32_e32 v4, v3, v0
	v_cndmask_b32_e32 v3, v3, v4, vcc
	v_cmp_ge_u32_e32 vcc, v3, v0
	v_add_u32_e32 v3, 1, v2
	s_nop 0
	v_cndmask_b32_e32 v2, v2, v3, vcc
	v_mul_lo_u32 v3, v0, v2
	v_add_u32_e32 v0, v3, v0
	v_cmp_ne_u32_e32 vcc, v1, v0
	v_mov_b64_e32 v[0:1], s[6:7]
	s_and_saveexec_b64 s[12:13], vcc
	s_cbranch_execz .LBB0_1184
	v_readlane_b32 s100, v252, 9
	s_nop 3
	v_mov_b32_e32 v18, s100
	ds_read_b32 v18, v18
	v_add_u32_e32 v19, 1, v2
	s_waitcnt lgkmcnt(0)
	v_mul_lo_u32 v18, v18, v19
	v_readlane_b32 s6, v253, 20
	v_readlane_b32 s7, v253, 21
	s_mov_b64 s[20:21], 0
	s_nop 3
	global_load_dword v0, v64, s[6:7] sc1
	s_waitcnt vmcnt(0)
	v_cmp_lt_u32_e32 vcc, v0, v18
	s_and_saveexec_b64 s[16:17], vcc
	s_cbranch_execz .LBB0_1183
	s_mov_b32 s6, 1
	s_branch .LBB0_1176

.LBB0_1797:
	s_or_b64 exec, exec, s[12:13]
	v_cvt_f32_u32_e32 v4, v2
	s_waitcnt vmcnt(0)
	v_readfirstlane_b32 s2, v3
	v_sub_u32_e32 v3, 0, v2
	v_rcp_iflag_f32_e32 v4, v4
	v_add_u32_e32 v5, s2, v1
	v_mul_f32_e32 v4, 0x4f7ffffe, v4
	v_cvt_u32_f32_e32 v4, v4
	v_mul_lo_u32 v1, v3, v4
	v_mul_hi_u32 v1, v4, v1
	v_add_u32_e32 v1, v4, v1
	v_mul_hi_u32 v1, v5, v1
	v_mul_lo_u32 v3, v1, v2
	v_sub_u32_e32 v3, v5, v3
	v_add_u32_e32 v4, 1, v1
	v_cmp_ge_u32_e32 vcc, v3, v2
	s_nop 1
	v_cndmask_b32_e32 v1, v1, v4, vcc
	v_sub_u32_e32 v4, v3, v2
	v_cndmask_b32_e32 v3, v3, v4, vcc
	v_add_u32_e32 v4, 1, v1
	v_cmp_ge_u32_e32 vcc, v3, v2
	v_add_u32_e32 v3, 1, v5
	s_nop 0
	v_cndmask_b32_e32 v1, v1, v4, vcc
	v_mul_lo_u32 v4, v2, v1
	v_add_u32_e32 v2, v4, v2
	v_cmp_ne_u32_e32 vcc, v3, v2
	s_and_saveexec_b64 s[2:3], vcc
	s_xor_b64 s[12:13], exec, s[2:3]
	s_cbranch_execz .LBB0_1811
	v_readlane_b32 s100, v252, 9
	s_nop 3
	v_mov_b32_e32 v18, s100
	ds_read_b32 v18, v18
	v_add_u32_e32 v19, 1, v1
	s_waitcnt lgkmcnt(0)
	v_mul_lo_u32 v18, v18, v19
	v_readlane_b32 s2, v253, 20
	v_readlane_b32 s3, v253, 21
	s_waitcnt lgkmcnt(0)
	s_nop 3
	buffer_inv sc1
	global_load_dword v0, v64, s[2:3] sc1
	s_waitcnt vmcnt(0)
	v_cmp_lt_u32_e32 vcc, v0, v18
	s_and_saveexec_b64 s[20:21], vcc
	s_cbranch_execz .LBB0_1810
	s_mov_b32 s2, 1
	s_mov_b64 s[28:29], 0
	s_branch .LBB0_1801

.LBB0_1803:
	v_readlane_b32 s6, v253, 20
	v_readlane_b32 s7, v253, 21
	s_add_i32 s2, s2, 1
	s_mov_b64 s[46:47], -1
	s_nop 2
	global_load_dword v0, v64, s[6:7] sc1
	s_waitcnt vmcnt(0)
	v_cmp_ge_u32_e32 vcc, v0, v18
	s_orn2_b64 s[44:45], vcc, exec
	s_branch .LBB0_1800

.LBB0_1814:
	s_or_b64 exec, exec, s[20:21]
	s_waitcnt vmcnt(0)
	v_readfirstlane_b32 s2, v2
	v_cvt_f32_u32_e32 v2, v0
	v_sub_u32_e32 v3, 0, v0
	v_add_u32_e32 v1, s2, v1
	v_readlane_b32 s2, v253, 22
	v_rcp_iflag_f32_e32 v2, v2
	v_readlane_b32 s3, v253, 23
	s_mov_b64 s[20:21], -1
	v_mul_f32_e32 v2, 0x4f7ffffe, v2
	v_cvt_u32_f32_e32 v2, v2
	v_mul_lo_u32 v3, v3, v2
	v_mul_hi_u32 v3, v2, v3
	v_add_u32_e32 v2, v2, v3
	v_mul_hi_u32 v2, v1, v2
	v_mul_lo_u32 v3, v2, v0
	v_sub_u32_e32 v3, v1, v3
	v_cmp_ge_u32_e32 vcc, v3, v0
	v_add_u32_e32 v4, 1, v2
	v_add_u32_e32 v1, 1, v1
	v_cndmask_b32_e32 v2, v2, v4, vcc
	v_sub_u32_e32 v4, v3, v0
	v_cndmask_b32_e32 v3, v3, v4, vcc
	v_cmp_ge_u32_e32 vcc, v3, v0
	v_add_u32_e32 v3, 1, v2
	s_nop 0
	v_cndmask_b32_e32 v2, v2, v3, vcc
	v_mul_lo_u32 v3, v0, v2
	v_add_u32_e32 v0, v3, v0
	v_cmp_ne_u32_e32 vcc, v1, v0
	v_mov_b64_e32 v[0:1], s[2:3]
	s_and_saveexec_b64 s[12:13], vcc
	s_cbranch_execz .LBB0_1826
	v_readlane_b32 s100, v252, 9
	s_nop 3
	v_mov_b32_e32 v18, s100
	ds_read_b32 v18, v18
	v_add_u32_e32 v19, 1, v2
	s_waitcnt lgkmcnt(0)
	v_mul_lo_u32 v18, v18, v19
	v_readlane_b32 s2, v253, 20
	v_readlane_b32 s3, v253, 21
	s_mov_b64 s[28:29], 0
	s_nop 3
	global_load_dword v0, v64, s[2:3] sc1
	s_waitcnt vmcnt(0)
	v_cmp_lt_u32_e32 vcc, v0, v18
	s_and_saveexec_b64 s[20:21], vcc
	s_cbranch_execz .LBB0_1825
	s_mov_b32 s2, 1
	s_branch .LBB0_1818

.LBB0_1924:
	s_or_b64 exec, exec, s[12:13]
	v_cvt_f32_u32_e32 v4, v2
	s_waitcnt vmcnt(0)
	v_readfirstlane_b32 s2, v3
	v_sub_u32_e32 v3, 0, v2
	v_rcp_iflag_f32_e32 v4, v4
	v_add_u32_e32 v5, s2, v1
	v_mul_f32_e32 v4, 0x4f7ffffe, v4
	v_cvt_u32_f32_e32 v4, v4
	v_mul_lo_u32 v1, v3, v4
	v_mul_hi_u32 v1, v4, v1
	v_add_u32_e32 v1, v4, v1
	v_mul_hi_u32 v1, v5, v1
	v_mul_lo_u32 v3, v1, v2
	v_sub_u32_e32 v3, v5, v3
	v_add_u32_e32 v4, 1, v1
	v_cmp_ge_u32_e32 vcc, v3, v2
	s_nop 1
	v_cndmask_b32_e32 v1, v1, v4, vcc
	v_sub_u32_e32 v4, v3, v2
	v_cndmask_b32_e32 v3, v3, v4, vcc
	v_add_u32_e32 v4, 1, v1
	v_cmp_ge_u32_e32 vcc, v3, v2
	v_add_u32_e32 v3, 1, v5
	s_nop 0
	v_cndmask_b32_e32 v1, v1, v4, vcc
	v_mul_lo_u32 v4, v2, v1
	v_add_u32_e32 v2, v4, v2
	v_cmp_ne_u32_e32 vcc, v3, v2
	s_and_saveexec_b64 s[2:3], vcc
	s_xor_b64 s[12:13], exec, s[2:3]
	s_cbranch_execz .LBB0_1938
	v_readlane_b32 s100, v252, 9
	s_nop 3
	v_mov_b32_e32 v18, s100
	ds_read_b32 v18, v18
	v_add_u32_e32 v19, 1, v1
	s_waitcnt lgkmcnt(0)
	v_mul_lo_u32 v18, v18, v19
	v_readlane_b32 s2, v253, 20
	v_readlane_b32 s3, v253, 21
	s_waitcnt lgkmcnt(0)
	s_nop 3
	buffer_inv sc1
	global_load_dword v0, v64, s[2:3] sc1
	s_waitcnt vmcnt(0)
	v_cmp_lt_u32_e32 vcc, v0, v18
	s_and_saveexec_b64 s[20:21], vcc
	s_cbranch_execz .LBB0_1937
	s_mov_b32 s2, 1
	s_mov_b64 s[42:43], 0
	s_branch .LBB0_1928

.LBB0_1930:
	v_readlane_b32 s6, v253, 20
	v_readlane_b32 s7, v253, 21
	s_add_i32 s2, s2, 1
	s_mov_b64 s[48:49], -1
	s_nop 2
	global_load_dword v0, v64, s[6:7] sc1
	s_waitcnt vmcnt(0)
	v_cmp_ge_u32_e32 vcc, v0, v18
	s_orn2_b64 s[46:47], vcc, exec
	s_branch .LBB0_1927

.LBB0_1941:
	s_or_b64 exec, exec, s[20:21]
	s_waitcnt vmcnt(0)
	v_readfirstlane_b32 s2, v2
	v_cvt_f32_u32_e32 v2, v0
	v_sub_u32_e32 v3, 0, v0
	v_add_u32_e32 v1, s2, v1
	v_readlane_b32 s2, v253, 22
	v_rcp_iflag_f32_e32 v2, v2
	v_readlane_b32 s3, v253, 23
	s_mov_b64 s[20:21], -1
	v_mul_f32_e32 v2, 0x4f7ffffe, v2
	v_cvt_u32_f32_e32 v2, v2
	v_mul_lo_u32 v3, v3, v2
	v_mul_hi_u32 v3, v2, v3
	v_add_u32_e32 v2, v2, v3
	v_mul_hi_u32 v2, v1, v2
	v_mul_lo_u32 v3, v2, v0
	v_sub_u32_e32 v3, v1, v3
	v_cmp_ge_u32_e32 vcc, v3, v0
	v_add_u32_e32 v4, 1, v2
	v_add_u32_e32 v1, 1, v1
	v_cndmask_b32_e32 v2, v2, v4, vcc
	v_sub_u32_e32 v4, v3, v0
	v_cndmask_b32_e32 v3, v3, v4, vcc
	v_cmp_ge_u32_e32 vcc, v3, v0
	v_add_u32_e32 v3, 1, v2
	s_nop 0
	v_cndmask_b32_e32 v2, v2, v3, vcc
	v_mul_lo_u32 v3, v0, v2
	v_add_u32_e32 v0, v3, v0
	v_cmp_ne_u32_e32 vcc, v1, v0
	v_mov_b64_e32 v[0:1], s[2:3]
	s_and_saveexec_b64 s[12:13], vcc
	s_cbranch_execz .LBB0_1953
	v_readlane_b32 s100, v252, 9
	s_nop 3
	v_mov_b32_e32 v18, s100
	ds_read_b32 v18, v18
	v_add_u32_e32 v19, 1, v2
	s_waitcnt lgkmcnt(0)
	v_mul_lo_u32 v18, v18, v19
	v_readlane_b32 s2, v253, 20
	v_readlane_b32 s3, v253, 21
	s_mov_b64 s[42:43], 0
	s_nop 3
	global_load_dword v0, v64, s[2:3] sc1
	s_waitcnt vmcnt(0)
	v_cmp_lt_u32_e32 vcc, v0, v18
	s_and_saveexec_b64 s[20:21], vcc
	s_cbranch_execz .LBB0_1952
	s_mov_b32 s2, 1
	s_branch .LBB0_1945

.LBB0_2187:
	s_or_b64 exec, exec, s[12:13]
	v_cvt_f32_u32_e32 v4, v2
	s_waitcnt vmcnt(0)
	v_readfirstlane_b32 s2, v3
	v_sub_u32_e32 v3, 0, v2
	v_rcp_iflag_f32_e32 v4, v4
	v_add_u32_e32 v5, s2, v1
	v_mul_f32_e32 v4, 0x4f7ffffe, v4
	v_cvt_u32_f32_e32 v4, v4
	v_mul_lo_u32 v1, v3, v4
	v_mul_hi_u32 v1, v4, v1
	v_add_u32_e32 v1, v4, v1
	v_mul_hi_u32 v1, v5, v1
	v_mul_lo_u32 v3, v1, v2
	v_sub_u32_e32 v3, v5, v3
	v_add_u32_e32 v4, 1, v1
	v_cmp_ge_u32_e32 vcc, v3, v2
	s_nop 1
	v_cndmask_b32_e32 v1, v1, v4, vcc
	v_sub_u32_e32 v4, v3, v2
	v_cndmask_b32_e32 v3, v3, v4, vcc
	v_add_u32_e32 v4, 1, v1
	v_cmp_ge_u32_e32 vcc, v3, v2
	v_add_u32_e32 v3, 1, v5
	s_nop 0
	v_cndmask_b32_e32 v1, v1, v4, vcc
	v_mul_lo_u32 v4, v2, v1
	v_add_u32_e32 v2, v4, v2
	v_cmp_ne_u32_e32 vcc, v3, v2
	s_and_saveexec_b64 s[2:3], vcc
	s_xor_b64 s[12:13], exec, s[2:3]
	s_cbranch_execz .LBB0_2201
	v_readlane_b32 s100, v252, 9
	s_nop 3
	v_mov_b32_e32 v18, s100
	ds_read_b32 v18, v18
	v_add_u32_e32 v19, 1, v1
	s_waitcnt lgkmcnt(0)
	v_mul_lo_u32 v18, v18, v19
	v_readlane_b32 s2, v253, 20
	v_readlane_b32 s3, v253, 21
	s_waitcnt lgkmcnt(0)
	s_nop 3
	buffer_inv sc1
	global_load_dword v0, v64, s[2:3] sc1
	s_waitcnt vmcnt(0)
	v_cmp_lt_u32_e32 vcc, v0, v18
	s_and_saveexec_b64 s[16:17], vcc
	s_cbranch_execz .LBB0_2200
	s_mov_b32 s2, 1
	s_mov_b64 s[20:21], 0
	s_branch .LBB0_2191

.LBB0_2193:
	v_readlane_b32 s38, v253, 20
	v_readlane_b32 s39, v253, 21
	s_add_i32 s2, s2, 1
	s_mov_b64 s[42:43], -1
	s_nop 2
	global_load_dword v0, v64, s[38:39] sc1
	s_waitcnt vmcnt(0)
	v_cmp_ge_u32_e32 vcc, v0, v18
	s_orn2_b64 s[40:41], vcc, exec
	s_branch .LBB0_2190

.LBB0_2204:
	s_or_b64 exec, exec, s[16:17]
	s_waitcnt vmcnt(0)
	v_readfirstlane_b32 s2, v2
	v_cvt_f32_u32_e32 v2, v0
	v_sub_u32_e32 v3, 0, v0
	v_add_u32_e32 v1, s2, v1
	v_readlane_b32 s2, v253, 22
	v_rcp_iflag_f32_e32 v2, v2
	v_readlane_b32 s3, v253, 23
	s_mov_b64 s[16:17], -1
	v_mul_f32_e32 v2, 0x4f7ffffe, v2
	v_cvt_u32_f32_e32 v2, v2
	v_mul_lo_u32 v3, v3, v2
	v_mul_hi_u32 v3, v2, v3
	v_add_u32_e32 v2, v2, v3
	v_mul_hi_u32 v2, v1, v2
	v_mul_lo_u32 v3, v2, v0
	v_sub_u32_e32 v3, v1, v3
	v_cmp_ge_u32_e32 vcc, v3, v0
	v_add_u32_e32 v4, 1, v2
	v_add_u32_e32 v1, 1, v1
	v_cndmask_b32_e32 v2, v2, v4, vcc
	v_sub_u32_e32 v4, v3, v0
	v_cndmask_b32_e32 v3, v3, v4, vcc
	v_cmp_ge_u32_e32 vcc, v3, v0
	v_add_u32_e32 v3, 1, v2
	s_nop 0
	v_cndmask_b32_e32 v2, v2, v3, vcc
	v_mul_lo_u32 v3, v0, v2
	v_add_u32_e32 v0, v3, v0
	v_cmp_ne_u32_e32 vcc, v1, v0
	v_mov_b64_e32 v[0:1], s[2:3]
	s_and_saveexec_b64 s[12:13], vcc
	s_cbranch_execz .LBB0_2216
	v_readlane_b32 s100, v252, 9
	s_nop 3
	v_mov_b32_e32 v18, s100
	ds_read_b32 v18, v18
	v_add_u32_e32 v19, 1, v2
	s_waitcnt lgkmcnt(0)
	v_mul_lo_u32 v18, v18, v19
	v_readlane_b32 s2, v253, 20
	v_readlane_b32 s3, v253, 21
	s_mov_b64 s[20:21], 0
	s_nop 3
	global_load_dword v0, v64, s[2:3] sc1
	s_waitcnt vmcnt(0)
	v_cmp_lt_u32_e32 vcc, v0, v18
	s_and_saveexec_b64 s[16:17], vcc
	s_cbranch_execz .LBB0_2215
	s_mov_b32 s2, 1
	s_branch .LBB0_2208

.LBB0_2261:
	s_or_b64 exec, exec, s[6:7]
	v_cvt_f32_u32_e32 v4, v2
	s_waitcnt vmcnt(0)
	v_readfirstlane_b32 s6, v3
	v_sub_u32_e32 v3, 0, v2
	v_rcp_iflag_f32_e32 v4, v4
	v_add_u32_e32 v5, s6, v1
	v_mul_f32_e32 v4, 0x4f7ffffe, v4
	v_cvt_u32_f32_e32 v4, v4
	v_mul_lo_u32 v1, v3, v4
	v_mul_hi_u32 v1, v4, v1
	v_add_u32_e32 v1, v4, v1
	v_mul_hi_u32 v1, v5, v1
	v_mul_lo_u32 v3, v1, v2
	v_sub_u32_e32 v3, v5, v3
	v_add_u32_e32 v4, 1, v1
	v_cmp_ge_u32_e32 vcc, v3, v2
	s_nop 1
	v_cndmask_b32_e32 v1, v1, v4, vcc
	v_sub_u32_e32 v4, v3, v2
	v_cndmask_b32_e32 v3, v3, v4, vcc
	v_add_u32_e32 v4, 1, v1
	v_cmp_ge_u32_e32 vcc, v3, v2
	v_add_u32_e32 v3, 1, v5
	s_nop 0
	v_cndmask_b32_e32 v1, v1, v4, vcc
	v_mul_lo_u32 v4, v2, v1
	v_add_u32_e32 v2, v4, v2
	v_cmp_ne_u32_e32 vcc, v3, v2
	s_and_saveexec_b64 s[6:7], vcc
	s_xor_b64 s[6:7], exec, s[6:7]
	s_cbranch_execz .LBB0_2275
	v_readlane_b32 s100, v252, 9
	s_nop 3
	v_mov_b32_e32 v18, s100
	ds_read_b32 v18, v18
	v_add_u32_e32 v19, 1, v1
	s_waitcnt lgkmcnt(0)
	v_mul_lo_u32 v18, v18, v19
	v_readlane_b32 s12, v253, 20
	v_readlane_b32 s13, v253, 21
	s_waitcnt lgkmcnt(0)
	s_nop 3
	buffer_inv sc1
	global_load_dword v0, v64, s[12:13] sc1
	s_waitcnt vmcnt(0)
	v_cmp_lt_u32_e32 vcc, v0, v18
	s_and_saveexec_b64 s[12:13], vcc
	s_cbranch_execz .LBB0_2274
	s_mov_b32 s18, 1
	s_mov_b64 s[16:17], 0
	s_branch .LBB0_2265

.LBB0_2267:
	v_readlane_b32 s28, v253, 20
	v_readlane_b32 s29, v253, 21
	s_add_i32 s18, s18, 1
	s_mov_b64 s[38:39], -1
	s_nop 2
	global_load_dword v0, v64, s[28:29] sc1
	s_waitcnt vmcnt(0)
	v_cmp_ge_u32_e32 vcc, v0, v18
	s_orn2_b64 s[28:29], vcc, exec
	s_branch .LBB0_2264

.LBB0_2278:
	s_or_b64 exec, exec, s[12:13]
	s_waitcnt vmcnt(0)
	v_readfirstlane_b32 s6, v2
	v_cvt_f32_u32_e32 v2, v0
	v_sub_u32_e32 v3, 0, v0
	v_add_u32_e32 v1, s6, v1
	v_readlane_b32 s6, v253, 22
	v_rcp_iflag_f32_e32 v2, v2
	v_readlane_b32 s7, v253, 23
	s_mov_b64 s[12:13], -1
	v_mul_f32_e32 v2, 0x4f7ffffe, v2
	v_cvt_u32_f32_e32 v2, v2
	v_mul_lo_u32 v3, v3, v2
	v_mul_hi_u32 v3, v2, v3
	v_add_u32_e32 v2, v2, v3
	v_mul_hi_u32 v2, v1, v2
	v_mul_lo_u32 v3, v2, v0
	v_sub_u32_e32 v3, v1, v3
	v_cmp_ge_u32_e32 vcc, v3, v0
	v_add_u32_e32 v4, 1, v2
	v_add_u32_e32 v1, 1, v1
	v_cndmask_b32_e32 v2, v2, v4, vcc
	v_sub_u32_e32 v4, v3, v0
	v_cndmask_b32_e32 v3, v3, v4, vcc
	v_cmp_ge_u32_e32 vcc, v3, v0
	v_add_u32_e32 v3, 1, v2
	s_nop 0
	v_cndmask_b32_e32 v2, v2, v3, vcc
	v_mul_lo_u32 v3, v0, v2
	v_add_u32_e32 v0, v3, v0
	v_cmp_ne_u32_e32 vcc, v1, v0
	v_mov_b64_e32 v[0:1], s[6:7]
	s_and_saveexec_b64 s[6:7], vcc
	s_cbranch_execz .LBB0_2290
	v_readlane_b32 s100, v252, 9
	s_nop 3
	v_mov_b32_e32 v18, s100
	ds_read_b32 v18, v18
	v_add_u32_e32 v19, 1, v2
	s_waitcnt lgkmcnt(0)
	v_mul_lo_u32 v18, v18, v19
	v_readlane_b32 s12, v253, 20
	v_readlane_b32 s13, v253, 21
	s_mov_b64 s[16:17], 0
	s_nop 3
	global_load_dword v0, v64, s[12:13] sc1
	s_waitcnt vmcnt(0)
	v_cmp_lt_u32_e32 vcc, v0, v18
	s_and_saveexec_b64 s[12:13], vcc
	s_cbranch_execz .LBB0_2289
	s_mov_b32 s18, 1
	s_branch .LBB0_2282
